# peer_v rewrite + gemm1 2-step DMA lead + peer_a next-token prefetch (no prep change)
# speedup vs baseline: 1.0070x; 1.0070x over previous
; DI int otid() { int t; asm volatile("v_mov_b32 %0, %1" : "=v"(t) : "v"((int)threadIdx.x)); return t; }
; template <bool RESCALE, bool SWAP>
; DI void gemm_mainloop_glds(const bf16_t* __restrict__ A, const bf16_t* __restrict__ Bt, int m0, int n0, char* lds,
;                            f32x16 (&acc)[2][2], const float* ratio_lds) {
;   constexpr int K = 1024, NK = K / 64, OPB = 16384, STB = 2 * OPB;
;   const int tid = otid(), lane = tid & 63, w = tid >> 6, wm = w >> 1, wn = w & 1, l31 = lane & 31, h = lane >> 5;
;   const int lr = lane >> 3, csrc = (lane & 7) ^ (4 * (w & 1) + (lr >> 1));
;   const bf16_t* ag = A + (size_t)(m0 + 8 * w + lr) * K + csrc * 8;
;   const bf16_t* bg = Bt + (size_t)(n0 + 8 * w + lr) * K + csrc * 8;
;   const unsigned lbase = (unsigned)(size_t)lds + (unsigned)w * 1024u;
;   const int swz = (l31 >> 1) & 7;
;   const char* fa = lds + (64 * wm + l31) * 128;
;   const char* fb = lds + OPB + (64 * wn + l31) * 128;
;   int fo[4];
; #pragma unroll
;   for (int s_ = 0; s_ < 4; ++s_) fo[s_] = ((2 * s_ + h) ^ swz) * 16;
;   f32x16 c00, c01, c10, c11;
; #pragma unroll
;   for (int r = 0; r < 16; ++r) { c00[r] = 0.f; c01[r] = 0.f; c10[r] = 0.f; c11[r] = 0.f; }
;     ...
;   D_ISSUE(0, 0);
;   __syncthreads();
; #pragma unroll 1
;   for (int kt = 0; kt < NK; kt += 2) {
;     D_ISSUE(1, kt + 1);
.LBB0_178:
	s_mov_b64 s[76:77], -1
	s_and_b64 vcc, exec, s[38:39]
	s_cbranch_vccz .LBB0_170
	s_lshl_b32 s84, s24, 7
	s_lshl_b32 s76, s85, 7
	s_cmp_eq_u32 s85, 5
	s_cselect_b64 s[38:39], -1, 0
	s_cmp_gt_i32 s85, 13
	s_cselect_b64 s[78:79], -1, 0
	s_or_b64 vcc, s[38:39], s[78:79]
	s_mov_b64 s[78:79], -1
	s_and_b64 vcc, exec, vcc
	s_cbranch_vccnz .LBB0_185
	v_readlane_b32 s78, v182, 19
	v_readlane_b32 s79, v182, 20
	v_lshrrev_b32_e32 v119, 3, v118
	v_lshrrev_b32_e32 v120, 6, v118
	v_and_b32_e32 v121, 1, v120
	v_bfe_u32 v122, v118, 4, 2
	v_lshl_or_b32 v122, v121, 2, v122
	v_and_b32_e32 v123, 7, v118
	v_xor_b32_e32 v122, v122, v123
	v_lshlrev_b32_e32 v124, 10, v120
	v_add_u32_e32 v126, s84, v119
	v_add_u32_e32 v128, s76, v119
	v_readfirstlane_b32 s86, v124
	v_lshlrev_b32_e32 v126, 11, v126
	v_lshlrev_b32_e32 v128, 11, v128
	v_lshl_or_b32 v126, v122, 4, v126
	v_lshl_or_b32 v128, v122, 4, v128
	v_mov_b32_e32 v127, 0
	v_mov_b32_e32 v129, 0
	v_lshl_add_u64 v[90:91], v[126:127], 0, s[78:79]
	v_lshl_add_u64 v[92:93], v[128:129], 0, s[20:21]
	v_lshl_add_u64 v[94:95], v[90:91], 0, s[34:35]
	v_lshl_add_u64 v[102:103], v[90:91], 0, s[40:41]
	v_lshl_add_u64 v[106:107], v[90:91], 0, s[42:43]
	v_lshl_add_u64 v[96:97], v[92:93], 0, s[34:35]
	v_lshl_add_u64 v[104:105], v[92:93], 0, s[40:41]
	v_lshl_add_u64 v[108:109], v[92:93], 0, s[42:43]
	v_mov_b32_e32 v130, 0x80
	v_mov_b32_e32 v131, 0
	s_mov_b32 m0, s86
	s_nop 0
	global_load_lds_dwordx4 v[90:91], off
	s_add_u32 m0, s86, 0x4000
	s_nop 0
	global_load_lds_dwordx4 v[92:93], off
	s_add_u32 m0, s86, 0x1000
	s_nop 0
	global_load_lds_dwordx4 v[94:95], off
	s_add_u32 m0, s86, 0x5000
	s_nop 0
	global_load_lds_dwordx4 v[96:97], off
	s_add_u32 m0, s86, 0x2000
	s_nop 0
	global_load_lds_dwordx4 v[102:103], off
	s_add_u32 m0, s86, 0x6000
	s_nop 0
	global_load_lds_dwordx4 v[104:105], off
	s_add_u32 m0, s86, 0x3000
	s_nop 0
	global_load_lds_dwordx4 v[106:107], off
	s_add_u32 m0, s86, 0x7000
	s_nop 0
	global_load_lds_dwordx4 v[108:109], off
	s_add_u32 m0, s86, 0x8000
	v_lshl_add_u64 v[90:91], v[130:131], 0, v[90:91]
	global_load_lds_dwordx4 v[90:91], off
	s_add_u32 m0, s86, 0xc000
	v_lshl_add_u64 v[92:93], v[130:131], 0, v[92:93]
	global_load_lds_dwordx4 v[92:93], off
	s_add_u32 m0, s86, 0x9000
	v_lshl_add_u64 v[94:95], v[130:131], 0, v[94:95]
	global_load_lds_dwordx4 v[94:95], off
	s_add_u32 m0, s86, 0xd000
	v_lshl_add_u64 v[96:97], v[130:131], 0, v[96:97]
	global_load_lds_dwordx4 v[96:97], off
	s_add_u32 m0, s86, 0xa000
	v_lshl_add_u64 v[102:103], v[130:131], 0, v[102:103]
	global_load_lds_dwordx4 v[102:103], off
	s_add_u32 m0, s86, 0xe000
	v_lshl_add_u64 v[104:105], v[130:131], 0, v[104:105]
	global_load_lds_dwordx4 v[104:105], off
	s_add_u32 m0, s86, 0xb000
	v_lshl_add_u64 v[106:107], v[130:131], 0, v[106:107]
	global_load_lds_dwordx4 v[106:107], off
	s_add_u32 m0, s86, 0xf000
	v_lshl_add_u64 v[108:109], v[130:131], 0, v[108:109]
	global_load_lds_dwordx4 v[108:109], off
	v_and_b32_e32 v119, 31, v118
	v_bfe_u32 v120, v118, 5, 1
	v_bfe_u32 v121, v118, 1, 3
	v_lshrrev_b32_e32 v122, 7, v118
	v_bfe_u32 v123, v118, 6, 1
	v_lshl_or_b32 v122, v122, 6, v119
	v_lshl_or_b32 v123, v123, 6, v119
	v_lshlrev_b32_e32 v122, 7, v122
	v_lshlrev_b32_e32 v123, 7, v123
	v_or_b32_e32 v124, 0, v120
	v_xor_b32_e32 v124, v124, v121
	v_lshl_add_u32 v110, v124, 4, v122
	v_lshl_add_u32 v114, v124, 4, v123
	v_or_b32_e32 v124, 2, v120
	v_xor_b32_e32 v124, v124, v121
	v_lshl_add_u32 v111, v124, 4, v122
	v_lshl_add_u32 v115, v124, 4, v123
	v_or_b32_e32 v124, 4, v120
	v_xor_b32_e32 v124, v124, v121
	v_lshl_add_u32 v112, v124, 4, v122
	v_lshl_add_u32 v116, v124, 4, v123
	v_or_b32_e32 v124, 6, v120
	v_xor_b32_e32 v124, v124, v121
	v_lshl_add_u32 v113, v124, 4, v122
	v_lshl_add_u32 v117, v124, 4, v123
	v_mov_b32_e32 v48, 0
	v_mov_b32_e32 v49, 0
	v_mov_b32_e32 v50, 0
	v_mov_b32_e32 v51, 0
	v_mov_b32_e32 v52, 0
	v_mov_b32_e32 v53, 0
	v_mov_b32_e32 v54, 0
	v_mov_b32_e32 v55, 0
	v_mov_b32_e32 v56, 0
	v_mov_b32_e32 v57, 0
	v_mov_b32_e32 v58, 0
	v_mov_b32_e32 v59, 0
	v_mov_b32_e32 v60, 0
	v_mov_b32_e32 v61, 0
	v_mov_b32_e32 v62, 0
	v_mov_b32_e32 v63, 0
	v_mov_b32_e32 v32, 0
	v_mov_b32_e32 v33, 0
	v_mov_b32_e32 v34, 0
	v_mov_b32_e32 v35, 0
	v_mov_b32_e32 v36, 0
	v_mov_b32_e32 v37, 0
	v_mov_b32_e32 v38, 0
	v_mov_b32_e32 v39, 0
	v_mov_b32_e32 v40, 0
	v_mov_b32_e32 v41, 0
	v_mov_b32_e32 v42, 0
	v_mov_b32_e32 v43, 0
	v_mov_b32_e32 v44, 0
	v_mov_b32_e32 v45, 0
	v_mov_b32_e32 v46, 0
	v_mov_b32_e32 v47, 0
	v_mov_b32_e32 v16, 0
	v_mov_b32_e32 v17, 0
	v_mov_b32_e32 v18, 0
	v_mov_b32_e32 v19, 0
	v_mov_b32_e32 v20, 0
	v_mov_b32_e32 v21, 0
	v_mov_b32_e32 v22, 0
	v_mov_b32_e32 v23, 0
	v_mov_b32_e32 v24, 0
	v_mov_b32_e32 v25, 0
	v_mov_b32_e32 v26, 0
	v_mov_b32_e32 v27, 0
	v_mov_b32_e32 v28, 0
	v_mov_b32_e32 v29, 0
	v_mov_b32_e32 v30, 0
	v_mov_b32_e32 v31, 0
	v_mov_b32_e32 v0, 0
	v_mov_b32_e32 v1, 0
	v_mov_b32_e32 v2, 0
	v_mov_b32_e32 v3, 0
	v_mov_b32_e32 v4, 0
	v_mov_b32_e32 v5, 0
	v_mov_b32_e32 v6, 0
	v_mov_b32_e32 v7, 0
	v_mov_b32_e32 v8, 0
	v_mov_b32_e32 v9, 0
	v_mov_b32_e32 v10, 0
	v_mov_b32_e32 v11, 0
	v_mov_b32_e32 v12, 0
	v_mov_b32_e32 v13, 0
	v_mov_b32_e32 v14, 0
	v_mov_b32_e32 v15, 0
	s_mov_b32 s77, 0
	s_waitcnt vmcnt(8)
	s_barrier
; DI int crow(int r, int h) { return (r & 3) + 8 * (r >> 2) + 4 * h; }
; #define D_COMPUTE(BUF) { D_MMA1(BUF, 0) D_MMA1(BUF, 1) D_MMA1(BUF, 2) D_MMA1(BUF, 3) }
; template <bool RESCALE, bool SWAP>
; DI void gemm_mainloop_glds(const bf16_t* __restrict__ A, const bf16_t* __restrict__ Bt, int m0, int n0, char* lds,
;                            f32x16 (&acc)[2][2], const float* ratio_lds) {
;     ...
;   for (int kt = 0; kt < NK; kt += 2) {
;     D_ISSUE(1, kt + 1);
;     if (RESCALE) {
;       if (kt == NK / 2) {
;         if (SWAP) {
;           const float sc0_ = ratio_lds[64 * wm + l31], sc1_ = ratio_lds[64 * wm + 32 + l31];
; #pragma unroll
;           for (int r = 0; r < 16; ++r) { c00[r] *= sc0_; c10[r] *= sc0_; c01[r] *= sc1_; c11[r] *= sc1_; }
;         } else {
; #pragma unroll
;           for (int r = 0; r < 16; ++r) {
;             float sc0_ = ratio_lds[64 * wm + crow(r, h)], sc1_ = ratio_lds[64 * wm + 32 + crow(r, h)];
;             c00[r] *= sc0_; c01[r] *= sc0_; c10[r] *= sc1_; c11[r] *= sc1_;
;           }
;         }
;       }
;     }
;     D_COMPUTE(0);
;     __syncthreads();
;     if (kt + 2 < NK) D_ISSUE(0, kt + 2);
;     D_COMPUTE(1);
;     __syncthreads();
;   }
.Lgm_g1s_loop:
	ds_read_b128 v[184:187], v110
	ds_read_b128 v[188:191], v110 offset:4096
	ds_read_b128 v[192:195], v114 offset:16384
	ds_read_b128 v[196:199], v114 offset:20480
	ds_read_b128 v[200:203], v111
	ds_read_b128 v[204:207], v111 offset:4096
	ds_read_b128 v[208:211], v115 offset:16384
	ds_read_b128 v[212:215], v115 offset:20480
	ds_read_b128 v[216:219], v112
	ds_read_b128 v[220:223], v112 offset:4096
	ds_read_b128 v[224:227], v116 offset:16384
	ds_read_b128 v[228:231], v116 offset:20480
	ds_read_b128 v[232:235], v113
	ds_read_b128 v[236:239], v113 offset:4096
	ds_read_b128 v[240:243], v117 offset:16384
	ds_read_b128 v[244:247], v117 offset:20480
	s_waitcnt lgkmcnt(0)
	s_barrier
	s_mov_b32 m0, s86
	v_lshl_add_u64 v[90:91], v[130:131], 0, v[90:91]
	global_load_lds_dwordx4 v[90:91], off
	s_add_u32 m0, s86, 0x4000
	v_lshl_add_u64 v[92:93], v[130:131], 0, v[92:93]
	global_load_lds_dwordx4 v[92:93], off
	s_add_u32 m0, s86, 0x1000
	v_lshl_add_u64 v[94:95], v[130:131], 0, v[94:95]
	global_load_lds_dwordx4 v[94:95], off
	s_add_u32 m0, s86, 0x5000
	v_lshl_add_u64 v[96:97], v[130:131], 0, v[96:97]
	global_load_lds_dwordx4 v[96:97], off
	s_add_u32 m0, s86, 0x2000
	v_lshl_add_u64 v[102:103], v[130:131], 0, v[102:103]
	global_load_lds_dwordx4 v[102:103], off
	s_add_u32 m0, s86, 0x6000
	v_lshl_add_u64 v[104:105], v[130:131], 0, v[104:105]
	global_load_lds_dwordx4 v[104:105], off
	s_add_u32 m0, s86, 0x3000
	v_lshl_add_u64 v[106:107], v[130:131], 0, v[106:107]
	global_load_lds_dwordx4 v[106:107], off
	s_add_u32 m0, s86, 0x7000
	v_lshl_add_u64 v[108:109], v[130:131], 0, v[108:109]
	global_load_lds_dwordx4 v[108:109], off
	v_mfma_f32_32x32x16_bf16 v[48:63], v[192:195], v[184:187], v[48:63]
	v_mfma_f32_32x32x16_bf16 v[32:47], v[192:195], v[188:191], v[32:47]
	v_mfma_f32_32x32x16_bf16 v[16:31], v[196:199], v[184:187], v[16:31]
	v_mfma_f32_32x32x16_bf16 v[0:15], v[196:199], v[188:191], v[0:15]
	v_mfma_f32_32x32x16_bf16 v[48:63], v[208:211], v[200:203], v[48:63]
	v_mfma_f32_32x32x16_bf16 v[32:47], v[208:211], v[204:207], v[32:47]
	v_mfma_f32_32x32x16_bf16 v[16:31], v[212:215], v[200:203], v[16:31]
	v_mfma_f32_32x32x16_bf16 v[0:15], v[212:215], v[204:207], v[0:15]
	v_mfma_f32_32x32x16_bf16 v[48:63], v[224:227], v[216:219], v[48:63]
	v_mfma_f32_32x32x16_bf16 v[32:47], v[224:227], v[220:223], v[32:47]
	v_mfma_f32_32x32x16_bf16 v[16:31], v[228:231], v[216:219], v[16:31]
	v_mfma_f32_32x32x16_bf16 v[0:15], v[228:231], v[220:223], v[0:15]
	v_mfma_f32_32x32x16_bf16 v[48:63], v[240:243], v[232:235], v[48:63]
	v_mfma_f32_32x32x16_bf16 v[32:47], v[240:243], v[236:239], v[32:47]
	v_mfma_f32_32x32x16_bf16 v[16:31], v[244:247], v[232:235], v[16:31]
	v_mfma_f32_32x32x16_bf16 v[0:15], v[244:247], v[236:239], v[0:15]
	s_waitcnt vmcnt(8)
	s_barrier
	ds_read_b128 v[184:187], v110 offset:32768
	ds_read_b128 v[188:191], v110 offset:36864
	ds_read_b128 v[192:195], v114 offset:49152
	ds_read_b128 v[196:199], v114 offset:53248
	ds_read_b128 v[200:203], v111 offset:32768
	ds_read_b128 v[204:207], v111 offset:36864
	ds_read_b128 v[208:211], v115 offset:49152
	ds_read_b128 v[212:215], v115 offset:53248
	ds_read_b128 v[216:219], v112 offset:32768
	ds_read_b128 v[220:223], v112 offset:36864
	ds_read_b128 v[224:227], v116 offset:49152
	ds_read_b128 v[228:231], v116 offset:53248
	ds_read_b128 v[232:235], v113 offset:32768
	ds_read_b128 v[236:239], v113 offset:36864
	ds_read_b128 v[240:243], v117 offset:49152
	ds_read_b128 v[244:247], v117 offset:53248
	s_waitcnt lgkmcnt(0)
	s_barrier
	s_add_u32 m0, s86, 0x8000
	v_lshl_add_u64 v[90:91], v[130:131], 0, v[90:91]
	global_load_lds_dwordx4 v[90:91], off
	s_add_u32 m0, s86, 0xc000
	v_lshl_add_u64 v[92:93], v[130:131], 0, v[92:93]
	global_load_lds_dwordx4 v[92:93], off
	s_add_u32 m0, s86, 0x9000
	v_lshl_add_u64 v[94:95], v[130:131], 0, v[94:95]
	global_load_lds_dwordx4 v[94:95], off
	s_add_u32 m0, s86, 0xd000
	v_lshl_add_u64 v[96:97], v[130:131], 0, v[96:97]
	global_load_lds_dwordx4 v[96:97], off
	s_add_u32 m0, s86, 0xa000
	v_lshl_add_u64 v[102:103], v[130:131], 0, v[102:103]
	global_load_lds_dwordx4 v[102:103], off
	s_add_u32 m0, s86, 0xe000
	v_lshl_add_u64 v[104:105], v[130:131], 0, v[104:105]
	global_load_lds_dwordx4 v[104:105], off
	s_add_u32 m0, s86, 0xb000
	v_lshl_add_u64 v[106:107], v[130:131], 0, v[106:107]
	global_load_lds_dwordx4 v[106:107], off
	s_add_u32 m0, s86, 0xf000
	v_lshl_add_u64 v[108:109], v[130:131], 0, v[108:109]
	global_load_lds_dwordx4 v[108:109], off
	v_mfma_f32_32x32x16_bf16 v[48:63], v[192:195], v[184:187], v[48:63]
	v_mfma_f32_32x32x16_bf16 v[32:47], v[192:195], v[188:191], v[32:47]
	v_mfma_f32_32x32x16_bf16 v[16:31], v[196:199], v[184:187], v[16:31]
	v_mfma_f32_32x32x16_bf16 v[0:15], v[196:199], v[188:191], v[0:15]
	v_mfma_f32_32x32x16_bf16 v[48:63], v[208:211], v[200:203], v[48:63]
	v_mfma_f32_32x32x16_bf16 v[32:47], v[208:211], v[204:207], v[32:47]
	v_mfma_f32_32x32x16_bf16 v[16:31], v[212:215], v[200:203], v[16:31]
	v_mfma_f32_32x32x16_bf16 v[0:15], v[212:215], v[204:207], v[0:15]
	v_mfma_f32_32x32x16_bf16 v[48:63], v[224:227], v[216:219], v[48:63]
	v_mfma_f32_32x32x16_bf16 v[32:47], v[224:227], v[220:223], v[32:47]
	v_mfma_f32_32x32x16_bf16 v[16:31], v[228:231], v[216:219], v[16:31]
	v_mfma_f32_32x32x16_bf16 v[0:15], v[228:231], v[220:223], v[0:15]
	v_mfma_f32_32x32x16_bf16 v[48:63], v[240:243], v[232:235], v[48:63]
	v_mfma_f32_32x32x16_bf16 v[32:47], v[240:243], v[236:239], v[32:47]
	v_mfma_f32_32x32x16_bf16 v[16:31], v[244:247], v[232:235], v[16:31]
	v_mfma_f32_32x32x16_bf16 v[0:15], v[244:247], v[236:239], v[0:15]
	s_waitcnt vmcnt(8)
	s_barrier
; DI int crow(int r, int h) { return (r & 3) + 8 * (r >> 2) + 4 * h; }
; #define D_COMPUTE(BUF) { D_MMA1(BUF, 0) D_MMA1(BUF, 1) D_MMA1(BUF, 2) D_MMA1(BUF, 3) }
; template <bool RESCALE, bool SWAP>
; DI void gemm_mainloop_glds(const bf16_t* __restrict__ A, const bf16_t* __restrict__ Bt, int m0, int n0, char* lds,
;                            f32x16 (&acc)[2][2], const float* ratio_lds) {
;     ...
;   for (int kt = 0; kt < NK; kt += 2) {
;     D_ISSUE(1, kt + 1);
;     if (RESCALE) {
;       if (kt == NK / 2) {
;         if (SWAP) {
;           const float sc0_ = ratio_lds[64 * wm + l31], sc1_ = ratio_lds[64 * wm + 32 + l31];
; #pragma unroll
;           for (int r = 0; r < 16; ++r) { c00[r] *= sc0_; c10[r] *= sc0_; c01[r] *= sc1_; c11[r] *= sc1_; }
;         } else {
; #pragma unroll
;           for (int r = 0; r < 16; ++r) {
;             float sc0_ = ratio_lds[64 * wm + crow(r, h)], sc1_ = ratio_lds[64 * wm + 32 + crow(r, h)];
;             c00[r] *= sc0_; c01[r] *= sc0_; c10[r] *= sc1_; c11[r] *= sc1_;
;           }
;         }
;       }
;     }
;     D_COMPUTE(0);
;     __syncthreads();
;     if (kt + 2 < NK) D_ISSUE(0, kt + 2);
;     D_COMPUTE(1);
;     __syncthreads();
;   }
;   acc[0][0] = c00; acc[0][1] = c01; acc[1][0] = c10; acc[1][1] = c11;
	s_add_i32 s77, s77, 2
	s_cmp_lt_u32 s77, 14
	s_cbranch_scc1 .Lgm_g1s_loop
	ds_read_b128 v[184:187], v110
	ds_read_b128 v[188:191], v110 offset:4096
	ds_read_b128 v[192:195], v114 offset:16384
	ds_read_b128 v[196:199], v114 offset:20480
	ds_read_b128 v[200:203], v111
	ds_read_b128 v[204:207], v111 offset:4096
	ds_read_b128 v[208:211], v115 offset:16384
	ds_read_b128 v[212:215], v115 offset:20480
	ds_read_b128 v[216:219], v112
	ds_read_b128 v[220:223], v112 offset:4096
	ds_read_b128 v[224:227], v116 offset:16384
	ds_read_b128 v[228:231], v116 offset:20480
	ds_read_b128 v[232:235], v113
	ds_read_b128 v[236:239], v113 offset:4096
	ds_read_b128 v[240:243], v117 offset:16384
	ds_read_b128 v[244:247], v117 offset:20480
	s_waitcnt lgkmcnt(0)
	v_mfma_f32_32x32x16_bf16 v[48:63], v[192:195], v[184:187], v[48:63]
	v_mfma_f32_32x32x16_bf16 v[32:47], v[192:195], v[188:191], v[32:47]
	v_mfma_f32_32x32x16_bf16 v[16:31], v[196:199], v[184:187], v[16:31]
	v_mfma_f32_32x32x16_bf16 v[0:15], v[196:199], v[188:191], v[0:15]
	v_mfma_f32_32x32x16_bf16 v[48:63], v[208:211], v[200:203], v[48:63]
	v_mfma_f32_32x32x16_bf16 v[32:47], v[208:211], v[204:207], v[32:47]
	v_mfma_f32_32x32x16_bf16 v[16:31], v[212:215], v[200:203], v[16:31]
	v_mfma_f32_32x32x16_bf16 v[0:15], v[212:215], v[204:207], v[0:15]
	v_mfma_f32_32x32x16_bf16 v[48:63], v[224:227], v[216:219], v[48:63]
	v_mfma_f32_32x32x16_bf16 v[32:47], v[224:227], v[220:223], v[32:47]
	v_mfma_f32_32x32x16_bf16 v[16:31], v[228:231], v[216:219], v[16:31]
	v_mfma_f32_32x32x16_bf16 v[0:15], v[228:231], v[220:223], v[0:15]
	v_mfma_f32_32x32x16_bf16 v[48:63], v[240:243], v[232:235], v[48:63]
	v_mfma_f32_32x32x16_bf16 v[32:47], v[240:243], v[236:239], v[32:47]
	v_mfma_f32_32x32x16_bf16 v[16:31], v[244:247], v[232:235], v[16:31]
	v_mfma_f32_32x32x16_bf16 v[0:15], v[244:247], v[236:239], v[0:15]
	s_waitcnt vmcnt(0)
	s_barrier
	ds_read_b128 v[184:187], v110 offset:32768
	ds_read_b128 v[188:191], v110 offset:36864
	ds_read_b128 v[192:195], v114 offset:49152
	ds_read_b128 v[196:199], v114 offset:53248
	ds_read_b128 v[200:203], v111 offset:32768
	ds_read_b128 v[204:207], v111 offset:36864
	ds_read_b128 v[208:211], v115 offset:49152
	ds_read_b128 v[212:215], v115 offset:53248
	ds_read_b128 v[216:219], v112 offset:32768
	ds_read_b128 v[220:223], v112 offset:36864
	ds_read_b128 v[224:227], v116 offset:49152
	ds_read_b128 v[228:231], v116 offset:53248
	ds_read_b128 v[232:235], v113 offset:32768
	ds_read_b128 v[236:239], v113 offset:36864
	ds_read_b128 v[240:243], v117 offset:49152
	ds_read_b128 v[244:247], v117 offset:53248
	s_waitcnt lgkmcnt(0)
	s_barrier
	v_mfma_f32_32x32x16_bf16 v[48:63], v[192:195], v[184:187], v[48:63]
	v_mfma_f32_32x32x16_bf16 v[32:47], v[192:195], v[188:191], v[32:47]
	v_mfma_f32_32x32x16_bf16 v[16:31], v[196:199], v[184:187], v[16:31]
	v_mfma_f32_32x32x16_bf16 v[0:15], v[196:199], v[188:191], v[0:15]
	v_mfma_f32_32x32x16_bf16 v[48:63], v[208:211], v[200:203], v[48:63]
	v_mfma_f32_32x32x16_bf16 v[32:47], v[208:211], v[204:207], v[32:47]
	v_mfma_f32_32x32x16_bf16 v[16:31], v[212:215], v[200:203], v[16:31]
	v_mfma_f32_32x32x16_bf16 v[0:15], v[212:215], v[204:207], v[0:15]
	v_mfma_f32_32x32x16_bf16 v[48:63], v[224:227], v[216:219], v[48:63]
	v_mfma_f32_32x32x16_bf16 v[32:47], v[224:227], v[220:223], v[32:47]
	v_mfma_f32_32x32x16_bf16 v[16:31], v[228:231], v[216:219], v[16:31]
	v_mfma_f32_32x32x16_bf16 v[0:15], v[228:231], v[220:223], v[0:15]
	v_mfma_f32_32x32x16_bf16 v[48:63], v[240:243], v[232:235], v[48:63]
	v_mfma_f32_32x32x16_bf16 v[32:47], v[240:243], v[236:239], v[32:47]
	v_mfma_f32_32x32x16_bf16 v[16:31], v[244:247], v[232:235], v[16:31]
	v_mfma_f32_32x32x16_bf16 v[0:15], v[244:247], v[236:239], v[0:15]
	s_nop 7
	s_nop 7

; DI int otid() { int t; asm volatile("v_mov_b32 %0, %1" : "=v"(t) : "v"((int)threadIdx.x)); return t; }
; template <bool RESCALE, bool SWAP>
; DI void gemm_mainloop_glds(const bf16_t* __restrict__ A, const bf16_t* __restrict__ Bt, int m0, int n0, char* lds,
;                            f32x16 (&acc)[2][2], const float* ratio_lds) {
;   constexpr int K = 1024, NK = K / 64, OPB = 16384, STB = 2 * OPB;
;   const int tid = otid(), lane = tid & 63, w = tid >> 6, wm = w >> 1, wn = w & 1, l31 = lane & 31, h = lane >> 5;
;   const int lr = lane >> 3, csrc = (lane & 7) ^ (4 * (w & 1) + (lr >> 1));
;   const bf16_t* ag = A + (size_t)(m0 + 8 * w + lr) * K + csrc * 8;
;   const bf16_t* bg = Bt + (size_t)(n0 + 8 * w + lr) * K + csrc * 8;
;   const unsigned lbase = (unsigned)(size_t)lds + (unsigned)w * 1024u;
;   const int swz = (l31 >> 1) & 7;
;   const char* fa = lds + (64 * wm + l31) * 128;
;   const char* fb = lds + OPB + (64 * wn + l31) * 128;
;   int fo[4];
; #pragma unroll
;   for (int s_ = 0; s_ < 4; ++s_) fo[s_] = ((2 * s_ + h) ^ swz) * 16;
;   f32x16 c00, c01, c10, c11;
; #pragma unroll
;   for (int r = 0; r < 16; ++r) { c00[r] = 0.f; c01[r] = 0.f; c10[r] = 0.f; c11[r] = 0.f; }
;     ...
;   D_ISSUE(0, 0);
;   __syncthreads();
; #pragma unroll 1
;   for (int kt = 0; kt < NK; kt += 2) {
;     D_ISSUE(1, kt + 1);
.LBB0_185:
	s_and_b64 vcc, exec, s[78:79]
	s_cbranch_vccz .LBB0_169
	v_readlane_b32 s78, v182, 19
	v_readlane_b32 s79, v182, 20
	v_lshrrev_b32_e32 v119, 3, v118
	v_lshrrev_b32_e32 v120, 6, v118
	v_and_b32_e32 v121, 1, v120
	v_bfe_u32 v122, v118, 4, 2
	v_lshl_or_b32 v122, v121, 2, v122
	v_and_b32_e32 v123, 7, v118
	v_xor_b32_e32 v122, v122, v123
	v_lshlrev_b32_e32 v124, 10, v120
	v_add_u32_e32 v126, s84, v119
	v_add_u32_e32 v128, s76, v119
	v_readfirstlane_b32 s86, v124
	v_lshlrev_b32_e32 v126, 11, v126
	v_lshlrev_b32_e32 v128, 11, v128
	v_lshl_or_b32 v126, v122, 4, v126
	v_lshl_or_b32 v128, v122, 4, v128
	v_mov_b32_e32 v127, 0
	v_mov_b32_e32 v129, 0
	v_lshl_add_u64 v[90:91], v[126:127], 0, s[78:79]
	v_lshl_add_u64 v[92:93], v[128:129], 0, s[20:21]
	v_lshl_add_u64 v[94:95], v[90:91], 0, s[34:35]
	v_lshl_add_u64 v[102:103], v[90:91], 0, s[40:41]
	v_lshl_add_u64 v[106:107], v[90:91], 0, s[42:43]
	v_lshl_add_u64 v[96:97], v[92:93], 0, s[34:35]
	v_lshl_add_u64 v[104:105], v[92:93], 0, s[40:41]
	v_lshl_add_u64 v[108:109], v[92:93], 0, s[42:43]
	v_mov_b32_e32 v130, 0x80
	v_mov_b32_e32 v131, 0
	s_mov_b32 m0, s86
	s_nop 0
	global_load_lds_dwordx4 v[90:91], off
	s_add_u32 m0, s86, 0x4000
	s_nop 0
	global_load_lds_dwordx4 v[92:93], off
	s_add_u32 m0, s86, 0x1000
	s_nop 0
	global_load_lds_dwordx4 v[94:95], off
	s_add_u32 m0, s86, 0x5000
	s_nop 0
	global_load_lds_dwordx4 v[96:97], off
	s_add_u32 m0, s86, 0x2000
	s_nop 0
	global_load_lds_dwordx4 v[102:103], off
	s_add_u32 m0, s86, 0x6000
	s_nop 0
	global_load_lds_dwordx4 v[104:105], off
	s_add_u32 m0, s86, 0x3000
	s_nop 0
	global_load_lds_dwordx4 v[106:107], off
	s_add_u32 m0, s86, 0x7000
	s_nop 0
	global_load_lds_dwordx4 v[108:109], off
	s_add_u32 m0, s86, 0x8000
	v_lshl_add_u64 v[90:91], v[130:131], 0, v[90:91]
	global_load_lds_dwordx4 v[90:91], off
	s_add_u32 m0, s86, 0xc000
	v_lshl_add_u64 v[92:93], v[130:131], 0, v[92:93]
	global_load_lds_dwordx4 v[92:93], off
	s_add_u32 m0, s86, 0x9000
	v_lshl_add_u64 v[94:95], v[130:131], 0, v[94:95]
	global_load_lds_dwordx4 v[94:95], off
	s_add_u32 m0, s86, 0xd000
	v_lshl_add_u64 v[96:97], v[130:131], 0, v[96:97]
	global_load_lds_dwordx4 v[96:97], off
	s_add_u32 m0, s86, 0xa000
	v_lshl_add_u64 v[102:103], v[130:131], 0, v[102:103]
	global_load_lds_dwordx4 v[102:103], off
	s_add_u32 m0, s86, 0xe000
	v_lshl_add_u64 v[104:105], v[130:131], 0, v[104:105]
	global_load_lds_dwordx4 v[104:105], off
	s_add_u32 m0, s86, 0xb000
	v_lshl_add_u64 v[106:107], v[130:131], 0, v[106:107]
	global_load_lds_dwordx4 v[106:107], off
	s_add_u32 m0, s86, 0xf000
	v_lshl_add_u64 v[108:109], v[130:131], 0, v[108:109]
	global_load_lds_dwordx4 v[108:109], off
	v_and_b32_e32 v119, 31, v118
	v_bfe_u32 v120, v118, 5, 1
	v_bfe_u32 v121, v118, 1, 3
	v_lshrrev_b32_e32 v122, 7, v118
	v_bfe_u32 v123, v118, 6, 1
	v_lshl_or_b32 v122, v122, 6, v119
	v_lshl_or_b32 v123, v123, 6, v119
	v_lshlrev_b32_e32 v122, 7, v122
	v_lshlrev_b32_e32 v123, 7, v123
	v_or_b32_e32 v124, 0, v120
	v_xor_b32_e32 v124, v124, v121
	v_lshl_add_u32 v110, v124, 4, v122
	v_lshl_add_u32 v114, v124, 4, v123
	v_or_b32_e32 v124, 2, v120
	v_xor_b32_e32 v124, v124, v121
	v_lshl_add_u32 v111, v124, 4, v122
	v_lshl_add_u32 v115, v124, 4, v123
	v_or_b32_e32 v124, 4, v120
	v_xor_b32_e32 v124, v124, v121
	v_lshl_add_u32 v112, v124, 4, v122
	v_lshl_add_u32 v116, v124, 4, v123
	v_or_b32_e32 v124, 6, v120
	v_xor_b32_e32 v124, v124, v121
	v_lshl_add_u32 v113, v124, 4, v122
	v_lshl_add_u32 v117, v124, 4, v123
	v_mov_b32_e32 v32, 0
	v_mov_b32_e32 v33, 0
	v_mov_b32_e32 v34, 0
	v_mov_b32_e32 v35, 0
	v_mov_b32_e32 v36, 0
	v_mov_b32_e32 v37, 0
	v_mov_b32_e32 v38, 0
	v_mov_b32_e32 v39, 0
	v_mov_b32_e32 v40, 0
	v_mov_b32_e32 v41, 0
	v_mov_b32_e32 v42, 0
	v_mov_b32_e32 v43, 0
	v_mov_b32_e32 v44, 0
	v_mov_b32_e32 v45, 0
	v_mov_b32_e32 v46, 0
	v_mov_b32_e32 v47, 0
	v_mov_b32_e32 v0, 0
	v_mov_b32_e32 v1, 0
	v_mov_b32_e32 v2, 0
	v_mov_b32_e32 v3, 0
	v_mov_b32_e32 v4, 0
	v_mov_b32_e32 v5, 0
	v_mov_b32_e32 v6, 0
	v_mov_b32_e32 v7, 0
	v_mov_b32_e32 v8, 0
	v_mov_b32_e32 v9, 0
	v_mov_b32_e32 v10, 0
	v_mov_b32_e32 v11, 0
	v_mov_b32_e32 v12, 0
	v_mov_b32_e32 v13, 0
	v_mov_b32_e32 v14, 0
	v_mov_b32_e32 v15, 0
	v_mov_b32_e32 v48, 0
	v_mov_b32_e32 v49, 0
	v_mov_b32_e32 v50, 0
	v_mov_b32_e32 v51, 0
	v_mov_b32_e32 v52, 0
	v_mov_b32_e32 v53, 0
	v_mov_b32_e32 v54, 0
	v_mov_b32_e32 v55, 0
	v_mov_b32_e32 v56, 0
	v_mov_b32_e32 v57, 0
	v_mov_b32_e32 v58, 0
	v_mov_b32_e32 v59, 0
	v_mov_b32_e32 v60, 0
	v_mov_b32_e32 v61, 0
	v_mov_b32_e32 v62, 0
	v_mov_b32_e32 v63, 0
	v_mov_b32_e32 v16, 0
	v_mov_b32_e32 v17, 0
	v_mov_b32_e32 v18, 0
	v_mov_b32_e32 v19, 0
	v_mov_b32_e32 v20, 0
	v_mov_b32_e32 v21, 0
	v_mov_b32_e32 v22, 0
	v_mov_b32_e32 v23, 0
	v_mov_b32_e32 v24, 0
	v_mov_b32_e32 v25, 0
	v_mov_b32_e32 v26, 0
	v_mov_b32_e32 v27, 0
	v_mov_b32_e32 v28, 0
	v_mov_b32_e32 v29, 0
	v_mov_b32_e32 v30, 0
	v_mov_b32_e32 v31, 0
	s_mov_b32 s77, 0
	s_waitcnt vmcnt(8)
	s_barrier
; DI int crow(int r, int h) { return (r & 3) + 8 * (r >> 2) + 4 * h; }
; #define D_COMPUTE(BUF) { D_MMA1(BUF, 0) D_MMA1(BUF, 1) D_MMA1(BUF, 2) D_MMA1(BUF, 3) }
; template <bool RESCALE, bool SWAP>
; DI void gemm_mainloop_glds(const bf16_t* __restrict__ A, const bf16_t* __restrict__ Bt, int m0, int n0, char* lds,
;                            f32x16 (&acc)[2][2], const float* ratio_lds) {
;     ...
;   for (int kt = 0; kt < NK; kt += 2) {
;     D_ISSUE(1, kt + 1);
;     if (RESCALE) {
;       if (kt == NK / 2) {
;         if (SWAP) {
;           const float sc0_ = ratio_lds[64 * wm + l31], sc1_ = ratio_lds[64 * wm + 32 + l31];
; #pragma unroll
;           for (int r = 0; r < 16; ++r) { c00[r] *= sc0_; c10[r] *= sc0_; c01[r] *= sc1_; c11[r] *= sc1_; }
;         } else {
; #pragma unroll
;           for (int r = 0; r < 16; ++r) {
;             float sc0_ = ratio_lds[64 * wm + crow(r, h)], sc1_ = ratio_lds[64 * wm + 32 + crow(r, h)];
;             c00[r] *= sc0_; c01[r] *= sc0_; c10[r] *= sc1_; c11[r] *= sc1_;
;           }
;         }
;       }
;     }
;     D_COMPUTE(0);
;     __syncthreads();
;     if (kt + 2 < NK) D_ISSUE(0, kt + 2);
;     D_COMPUTE(1);
;     __syncthreads();
;   }
.Lgm_g1n_loop:
	ds_read_b128 v[184:187], v110
	ds_read_b128 v[188:191], v110 offset:4096
	ds_read_b128 v[192:195], v114 offset:16384
	ds_read_b128 v[196:199], v114 offset:20480
	ds_read_b128 v[200:203], v111
	ds_read_b128 v[204:207], v111 offset:4096
	ds_read_b128 v[208:211], v115 offset:16384
	ds_read_b128 v[212:215], v115 offset:20480
	ds_read_b128 v[216:219], v112
	ds_read_b128 v[220:223], v112 offset:4096
	ds_read_b128 v[224:227], v116 offset:16384
	ds_read_b128 v[228:231], v116 offset:20480
	ds_read_b128 v[232:235], v113
	ds_read_b128 v[236:239], v113 offset:4096
	ds_read_b128 v[240:243], v117 offset:16384
	ds_read_b128 v[244:247], v117 offset:20480
	s_waitcnt lgkmcnt(0)
	s_barrier
	s_mov_b32 m0, s86
	v_lshl_add_u64 v[90:91], v[130:131], 0, v[90:91]
	global_load_lds_dwordx4 v[90:91], off
	s_add_u32 m0, s86, 0x4000
	v_lshl_add_u64 v[92:93], v[130:131], 0, v[92:93]
	global_load_lds_dwordx4 v[92:93], off
	s_add_u32 m0, s86, 0x1000
	v_lshl_add_u64 v[94:95], v[130:131], 0, v[94:95]
	global_load_lds_dwordx4 v[94:95], off
	s_add_u32 m0, s86, 0x5000
	v_lshl_add_u64 v[96:97], v[130:131], 0, v[96:97]
	global_load_lds_dwordx4 v[96:97], off
	s_add_u32 m0, s86, 0x2000
	v_lshl_add_u64 v[102:103], v[130:131], 0, v[102:103]
	global_load_lds_dwordx4 v[102:103], off
	s_add_u32 m0, s86, 0x6000
	v_lshl_add_u64 v[104:105], v[130:131], 0, v[104:105]
	global_load_lds_dwordx4 v[104:105], off
	s_add_u32 m0, s86, 0x3000
	v_lshl_add_u64 v[106:107], v[130:131], 0, v[106:107]
	global_load_lds_dwordx4 v[106:107], off
	s_add_u32 m0, s86, 0x7000
	v_lshl_add_u64 v[108:109], v[130:131], 0, v[108:109]
	global_load_lds_dwordx4 v[108:109], off
	v_mfma_f32_32x32x16_bf16 v[32:47], v[184:187], v[192:195], v[32:47]
	v_mfma_f32_32x32x16_bf16 v[0:15], v[184:187], v[196:199], v[0:15]
	v_mfma_f32_32x32x16_bf16 v[48:63], v[188:191], v[192:195], v[48:63]
	v_mfma_f32_32x32x16_bf16 v[16:31], v[188:191], v[196:199], v[16:31]
	v_mfma_f32_32x32x16_bf16 v[32:47], v[200:203], v[208:211], v[32:47]
	v_mfma_f32_32x32x16_bf16 v[0:15], v[200:203], v[212:215], v[0:15]
	v_mfma_f32_32x32x16_bf16 v[48:63], v[204:207], v[208:211], v[48:63]
	v_mfma_f32_32x32x16_bf16 v[16:31], v[204:207], v[212:215], v[16:31]
	v_mfma_f32_32x32x16_bf16 v[32:47], v[216:219], v[224:227], v[32:47]
	v_mfma_f32_32x32x16_bf16 v[0:15], v[216:219], v[228:231], v[0:15]
	v_mfma_f32_32x32x16_bf16 v[48:63], v[220:223], v[224:227], v[48:63]
	v_mfma_f32_32x32x16_bf16 v[16:31], v[220:223], v[228:231], v[16:31]
	v_mfma_f32_32x32x16_bf16 v[32:47], v[232:235], v[240:243], v[32:47]
	v_mfma_f32_32x32x16_bf16 v[0:15], v[232:235], v[244:247], v[0:15]
	v_mfma_f32_32x32x16_bf16 v[48:63], v[236:239], v[240:243], v[48:63]
	v_mfma_f32_32x32x16_bf16 v[16:31], v[236:239], v[244:247], v[16:31]
	s_waitcnt vmcnt(8)
	s_barrier
	ds_read_b128 v[184:187], v110 offset:32768
	ds_read_b128 v[188:191], v110 offset:36864
	ds_read_b128 v[192:195], v114 offset:49152
	ds_read_b128 v[196:199], v114 offset:53248
	ds_read_b128 v[200:203], v111 offset:32768
	ds_read_b128 v[204:207], v111 offset:36864
	ds_read_b128 v[208:211], v115 offset:49152
	ds_read_b128 v[212:215], v115 offset:53248
	ds_read_b128 v[216:219], v112 offset:32768
	ds_read_b128 v[220:223], v112 offset:36864
	ds_read_b128 v[224:227], v116 offset:49152
	ds_read_b128 v[228:231], v116 offset:53248
	ds_read_b128 v[232:235], v113 offset:32768
	ds_read_b128 v[236:239], v113 offset:36864
	ds_read_b128 v[240:243], v117 offset:49152
	ds_read_b128 v[244:247], v117 offset:53248
	s_waitcnt lgkmcnt(0)
	s_barrier
	s_add_u32 m0, s86, 0x8000
	v_lshl_add_u64 v[90:91], v[130:131], 0, v[90:91]
	global_load_lds_dwordx4 v[90:91], off
	s_add_u32 m0, s86, 0xc000
	v_lshl_add_u64 v[92:93], v[130:131], 0, v[92:93]
	global_load_lds_dwordx4 v[92:93], off
	s_add_u32 m0, s86, 0x9000
	v_lshl_add_u64 v[94:95], v[130:131], 0, v[94:95]
	global_load_lds_dwordx4 v[94:95], off
	s_add_u32 m0, s86, 0xd000
	v_lshl_add_u64 v[96:97], v[130:131], 0, v[96:97]
	global_load_lds_dwordx4 v[96:97], off
	s_add_u32 m0, s86, 0xa000
	v_lshl_add_u64 v[102:103], v[130:131], 0, v[102:103]
	global_load_lds_dwordx4 v[102:103], off
	s_add_u32 m0, s86, 0xe000
	v_lshl_add_u64 v[104:105], v[130:131], 0, v[104:105]
	global_load_lds_dwordx4 v[104:105], off
	s_add_u32 m0, s86, 0xb000
	v_lshl_add_u64 v[106:107], v[130:131], 0, v[106:107]
	global_load_lds_dwordx4 v[106:107], off
	s_add_u32 m0, s86, 0xf000
	v_lshl_add_u64 v[108:109], v[130:131], 0, v[108:109]
	global_load_lds_dwordx4 v[108:109], off
	v_mfma_f32_32x32x16_bf16 v[32:47], v[184:187], v[192:195], v[32:47]
	v_mfma_f32_32x32x16_bf16 v[0:15], v[184:187], v[196:199], v[0:15]
	v_mfma_f32_32x32x16_bf16 v[48:63], v[188:191], v[192:195], v[48:63]
	v_mfma_f32_32x32x16_bf16 v[16:31], v[188:191], v[196:199], v[16:31]
	v_mfma_f32_32x32x16_bf16 v[32:47], v[200:203], v[208:211], v[32:47]
	v_mfma_f32_32x32x16_bf16 v[0:15], v[200:203], v[212:215], v[0:15]
	v_mfma_f32_32x32x16_bf16 v[48:63], v[204:207], v[208:211], v[48:63]
	v_mfma_f32_32x32x16_bf16 v[16:31], v[204:207], v[212:215], v[16:31]
	v_mfma_f32_32x32x16_bf16 v[32:47], v[216:219], v[224:227], v[32:47]
	v_mfma_f32_32x32x16_bf16 v[0:15], v[216:219], v[228:231], v[0:15]
	v_mfma_f32_32x32x16_bf16 v[48:63], v[220:223], v[224:227], v[48:63]
	v_mfma_f32_32x32x16_bf16 v[16:31], v[220:223], v[228:231], v[16:31]
	v_mfma_f32_32x32x16_bf16 v[32:47], v[232:235], v[240:243], v[32:47]
	v_mfma_f32_32x32x16_bf16 v[0:15], v[232:235], v[244:247], v[0:15]
	v_mfma_f32_32x32x16_bf16 v[48:63], v[236:239], v[240:243], v[48:63]
	v_mfma_f32_32x32x16_bf16 v[16:31], v[236:239], v[244:247], v[16:31]
	s_waitcnt vmcnt(8)
	s_barrier
; DI int crow(int r, int h) { return (r & 3) + 8 * (r >> 2) + 4 * h; }
; #define D_COMPUTE(BUF) { D_MMA1(BUF, 0) D_MMA1(BUF, 1) D_MMA1(BUF, 2) D_MMA1(BUF, 3) }
; template <bool RESCALE, bool SWAP>
; DI void gemm_mainloop_glds(const bf16_t* __restrict__ A, const bf16_t* __restrict__ Bt, int m0, int n0, char* lds,
;                            f32x16 (&acc)[2][2], const float* ratio_lds) {
;     ...
;   for (int kt = 0; kt < NK; kt += 2) {
;     D_ISSUE(1, kt + 1);
;     if (RESCALE) {
;       if (kt == NK / 2) {
;         if (SWAP) {
;           const float sc0_ = ratio_lds[64 * wm + l31], sc1_ = ratio_lds[64 * wm + 32 + l31];
; #pragma unroll
;           for (int r = 0; r < 16; ++r) { c00[r] *= sc0_; c10[r] *= sc0_; c01[r] *= sc1_; c11[r] *= sc1_; }
;         } else {
; #pragma unroll
;           for (int r = 0; r < 16; ++r) {
;             float sc0_ = ratio_lds[64 * wm + crow(r, h)], sc1_ = ratio_lds[64 * wm + 32 + crow(r, h)];
;             c00[r] *= sc0_; c01[r] *= sc0_; c10[r] *= sc1_; c11[r] *= sc1_;
;           }
;         }
;       }
;     }
;     D_COMPUTE(0);
;     __syncthreads();
;     if (kt + 2 < NK) D_ISSUE(0, kt + 2);
;     D_COMPUTE(1);
;     __syncthreads();
;   }
;   acc[0][0] = c00; acc[0][1] = c01; acc[1][0] = c10; acc[1][1] = c11;
	s_add_i32 s77, s77, 2
	s_cmp_lt_u32 s77, 14
	s_cbranch_scc1 .Lgm_g1n_loop
	ds_read_b128 v[184:187], v110
	ds_read_b128 v[188:191], v110 offset:4096
	ds_read_b128 v[192:195], v114 offset:16384
	ds_read_b128 v[196:199], v114 offset:20480
	ds_read_b128 v[200:203], v111
	ds_read_b128 v[204:207], v111 offset:4096
	ds_read_b128 v[208:211], v115 offset:16384
	ds_read_b128 v[212:215], v115 offset:20480
	ds_read_b128 v[216:219], v112
	ds_read_b128 v[220:223], v112 offset:4096
	ds_read_b128 v[224:227], v116 offset:16384
	ds_read_b128 v[228:231], v116 offset:20480
	ds_read_b128 v[232:235], v113
	ds_read_b128 v[236:239], v113 offset:4096
	ds_read_b128 v[240:243], v117 offset:16384
	ds_read_b128 v[244:247], v117 offset:20480
	s_waitcnt lgkmcnt(0)
	v_mfma_f32_32x32x16_bf16 v[32:47], v[184:187], v[192:195], v[32:47]
	v_mfma_f32_32x32x16_bf16 v[0:15], v[184:187], v[196:199], v[0:15]
	v_mfma_f32_32x32x16_bf16 v[48:63], v[188:191], v[192:195], v[48:63]
	v_mfma_f32_32x32x16_bf16 v[16:31], v[188:191], v[196:199], v[16:31]
	v_mfma_f32_32x32x16_bf16 v[32:47], v[200:203], v[208:211], v[32:47]
	v_mfma_f32_32x32x16_bf16 v[0:15], v[200:203], v[212:215], v[0:15]
	v_mfma_f32_32x32x16_bf16 v[48:63], v[204:207], v[208:211], v[48:63]
	v_mfma_f32_32x32x16_bf16 v[16:31], v[204:207], v[212:215], v[16:31]
	v_mfma_f32_32x32x16_bf16 v[32:47], v[216:219], v[224:227], v[32:47]
	v_mfma_f32_32x32x16_bf16 v[0:15], v[216:219], v[228:231], v[0:15]
	v_mfma_f32_32x32x16_bf16 v[48:63], v[220:223], v[224:227], v[48:63]
	v_mfma_f32_32x32x16_bf16 v[16:31], v[220:223], v[228:231], v[16:31]
	v_mfma_f32_32x32x16_bf16 v[32:47], v[232:235], v[240:243], v[32:47]
	v_mfma_f32_32x32x16_bf16 v[0:15], v[232:235], v[244:247], v[0:15]
	v_mfma_f32_32x32x16_bf16 v[48:63], v[236:239], v[240:243], v[48:63]
	v_mfma_f32_32x32x16_bf16 v[16:31], v[236:239], v[244:247], v[16:31]
	s_waitcnt vmcnt(0)
	s_barrier
	ds_read_b128 v[184:187], v110 offset:32768
	ds_read_b128 v[188:191], v110 offset:36864
	ds_read_b128 v[192:195], v114 offset:49152
	ds_read_b128 v[196:199], v114 offset:53248
	ds_read_b128 v[200:203], v111 offset:32768
	ds_read_b128 v[204:207], v111 offset:36864
	ds_read_b128 v[208:211], v115 offset:49152
	ds_read_b128 v[212:215], v115 offset:53248
	ds_read_b128 v[216:219], v112 offset:32768
	ds_read_b128 v[220:223], v112 offset:36864
	ds_read_b128 v[224:227], v116 offset:49152
	ds_read_b128 v[228:231], v116 offset:53248
	ds_read_b128 v[232:235], v113 offset:32768
	ds_read_b128 v[236:239], v113 offset:36864
	ds_read_b128 v[240:243], v117 offset:49152
	ds_read_b128 v[244:247], v117 offset:53248
	s_waitcnt lgkmcnt(0)
	s_barrier
	v_mfma_f32_32x32x16_bf16 v[32:47], v[184:187], v[192:195], v[32:47]
	v_mfma_f32_32x32x16_bf16 v[0:15], v[184:187], v[196:199], v[0:15]
	v_mfma_f32_32x32x16_bf16 v[48:63], v[188:191], v[192:195], v[48:63]
	v_mfma_f32_32x32x16_bf16 v[16:31], v[188:191], v[196:199], v[16:31]
	v_mfma_f32_32x32x16_bf16 v[32:47], v[200:203], v[208:211], v[32:47]
	v_mfma_f32_32x32x16_bf16 v[0:15], v[200:203], v[212:215], v[0:15]
	v_mfma_f32_32x32x16_bf16 v[48:63], v[204:207], v[208:211], v[48:63]
	v_mfma_f32_32x32x16_bf16 v[16:31], v[204:207], v[212:215], v[16:31]
	v_mfma_f32_32x32x16_bf16 v[32:47], v[216:219], v[224:227], v[32:47]
	v_mfma_f32_32x32x16_bf16 v[0:15], v[216:219], v[228:231], v[0:15]
	v_mfma_f32_32x32x16_bf16 v[48:63], v[220:223], v[224:227], v[48:63]
	v_mfma_f32_32x32x16_bf16 v[16:31], v[220:223], v[228:231], v[16:31]
	v_mfma_f32_32x32x16_bf16 v[32:47], v[232:235], v[240:243], v[32:47]
	v_mfma_f32_32x32x16_bf16 v[0:15], v[232:235], v[244:247], v[0:15]
	v_mfma_f32_32x32x16_bf16 v[48:63], v[236:239], v[240:243], v[48:63]
	v_mfma_f32_32x32x16_bf16 v[16:31], v[236:239], v[244:247], v[16:31]
	s_nop 7
	s_nop 7
	s_branch .LBB0_168

; DI float bflo(unsigned v) { return __uint_as_float(v << 16); }
; DI float bfhi(unsigned v) { return __uint_as_float(v & 0xffff0000u); }
; __device__ void phase_peer_a(const Params& p, int bid, int nb, char* lds) {
;     ...
;   for (int t = bid * 4 + w; t < NTOK; t += nb * 4) {
;     {
;       const u32x4* hp = (const u32x4*)(h2row + (size_t)t * 1024 + lane * 16);
;       const u32x4 a = hp[0], b = hp[1];
;       const u32x4 o = {pack_i8x4(bflo(a.x), bfhi(a.x), bflo(a.y), bfhi(a.y), XI8_SCALE), pack_i8x4(bflo(a.z), bfhi(a.z), bflo(a.w), bfhi(a.w), XI8_SCALE),
;                        pack_i8x4(bflo(b.x), bfhi(b.x), bflo(b.y), bfhi(b.y), XI8_SCALE), pack_i8x4(bflo(b.z), bfhi(b.z), bflo(b.w), bfhi(b.w), XI8_SCALE)};
;       *(u32x4*)((unsigned char*)(h2row + (size_t)t * 1024) + lane * 16) = o;
;     }
;     const size_t base = ((size_t)t * 16 + 2 * hd) * 16;
;     const float s1r0 = tops[base + sub], s1r1 = tops[base + sub + 8];
;     const int i1r0 = topi[base + sub] * 128, i1r1 = topi[base + sub + 8] * 128;
;     tab[sub] = make_uint2(__float_as_uint(tops[base + 16 + sub]), (unsigned)topi[base + 16 + sub]);
;     tab[sub + 8] = make_uint2(__float_as_uint(tops[base + 24 + sub]), (unsigned)topi[base + 24 + sub]);
.LBB0_525:
	s_or_b64 exec, exec, s[0:1]
	s_waitcnt lgkmcnt(0)
	v_mov_b32_e32 v0, 0x12400
	s_barrier
	ds_read_b32 v0, v0
	v_mov_b32_e32 v1, 0x12404
	ds_read_b32 v1, v1
	s_mov_b32 s0, 0x8000
	s_waitcnt lgkmcnt(1)
	v_readfirstlane_b32 s3, v0
	v_mov_b32_e32 v0, 0x12410
	ds_read_b32 v14, v0
	v_mov_b32 v0, v118
	s_waitcnt lgkmcnt(1)
	v_readfirstlane_b32 s56, v1
	v_ashrrev_i32_e32 v2, 6, v0
	v_add_u32_e32 v1, s24, v2
	v_cmp_gt_i32_e32 vcc, s0, v1
	s_and_saveexec_b64 s[18:19], vcc
	s_cbranch_execz .LBB0_558
	v_bfe_u32 v4, v0, 3, 3
	v_ashrrev_i32_e32 v3, 31, v2
	s_ashr_i32 s25, s24, 31
	v_and_b32_e32 v15, 7, v0
	v_lshlrev_b32_e32 v11, 7, v4
	v_lshl_add_u64 v[8:9], v[2:3], 0, s[24:25]
	v_lshl_or_b32 v16, v2, 10, v11
	v_lshlrev_b64 v[2:3], 9, v[8:9]
	v_lshlrev_b32_e32 v4, 6, v4
	v_lshlrev_b32_e32 v12, 2, v15
	v_and_b32_e32 v10, 63, v0
	v_or3_b32 v2, v4, v12, v2
	v_lshlrev_b64 v[4:5], 11, v[8:9]
	s_ashr_i32 s21, s20, 31
	v_lshl_or_b32 v6, v10, 4, v4
	v_mov_b32_e32 v7, v5
	s_mov_b64 s[26:27], 0x2b20000
	v_lshlrev_b64 v[8:9], 10, v[8:9]
	v_lshl_or_b32 v4, v10, 5, v4
	v_mbcnt_hi_u32_b32 v10, -1, v114
	v_and_b32_e32 v0, 56, v0
	v_lshl_or_b32 v17, v15, 3, v16
	v_mov_b32_e32 v18, 0
	v_cmp_eq_u32_e64 s[38:39], 0, v15
	v_cmp_eq_u32_e64 s[40:41], 1, v15
	v_cmp_eq_u32_e64 s[42:43], 2, v15
	v_cmp_eq_u32_e64 s[44:45], 3, v15
	v_cmp_eq_u32_e64 s[46:47], 4, v15
	v_cmp_eq_u32_e64 s[48:49], 5, v15
	v_cmp_eq_u32_e64 s[50:51], 6, v15
	v_cmp_eq_u32_e64 s[52:53], 7, v15
	s_lshl_b64 s[22:23], s[20:21], 9
	v_lshl_add_u64 v[6:7], v[6:7], 0, s[26:27]
	s_lshl_b64 s[28:29], s[20:21], 11
	v_or3_b32 v8, v11, v12, v8
	s_lshl_b64 s[30:31], s[20:21], 10
	s_mov_b64 s[34:35], 0
	s_movk_i32 s21, 0xff81
	v_mov_b32_e32 v19, 0x7f
	s_mov_b32 s25, 0x40c0c00
	v_and_b32_e32 v20, 64, v10
	v_lshl_add_u64 v[200:201], s[92:93], 0, v[4:5]
	v_lshl_add_u64 v[200:201], v[200:201], 0, s[26:27]
	global_load_dwordx4 v[184:187], v[200:201], off
	global_load_dwordx4 v[188:191], v[200:201], off offset:16
	v_lshl_add_u64 v[202:203], s[92:93], 0, v[8:9]
	v_add_co_u32_e32 v204, vcc, 0x6b20000, v202
	s_nop 1
	v_addc_co_u32_e32 v205, vcc, 0, v203, vcc
	v_add_co_u32_e32 v202, vcc, 0x8b20000, v202
	s_nop 1
	v_addc_co_u32_e32 v203, vcc, 0, v203, vcc
	global_load_dword v192, v[202:203], off offset:32
	global_load_dword v193, v[204:205], off offset:64
	global_load_dword v194, v[202:203], off offset:64
	global_load_dword v195, v[202:203], off offset:96
	global_load_dword v196, v[204:205], off offset:96
	global_load_dword v197, v[202:203], off
	global_load_dword v198, v[204:205], off
	global_load_dword v199, v[204:205], off offset:32
	s_branch .LBB0_528

; DI float bflo(unsigned v) { return __uint_as_float(v << 16); }
; DI float bfhi(unsigned v) { return __uint_as_float(v & 0xffff0000u); }
; __device__ void phase_peer_a(const Params& p, int bid, int nb, char* lds) {
;     ...
;     {
;       const u32x4* hp = (const u32x4*)(h2row + (size_t)t * 1024 + lane * 16);
;       const u32x4 a = hp[0], b = hp[1];
;       const u32x4 o = {pack_i8x4(bflo(a.x), bfhi(a.x), bflo(a.y), bfhi(a.y), XI8_SCALE), pack_i8x4(bflo(a.z), bfhi(a.z), bflo(a.w), bfhi(a.w), XI8_SCALE),
;                        pack_i8x4(bflo(b.x), bfhi(b.x), bflo(b.y), bfhi(b.y), XI8_SCALE), pack_i8x4(bflo(b.z), bfhi(b.z), bflo(b.w), bfhi(b.w), XI8_SCALE)};
;       *(u32x4*)((unsigned char*)(h2row + (size_t)t * 1024) + lane * 16) = o;
;     }
;     const size_t base = ((size_t)t * 16 + 2 * hd) * 16;
;     const float s1r0 = tops[base + sub], s1r1 = tops[base + sub + 8];
;     const int i1r0 = topi[base + sub] * 128, i1r1 = topi[base + sub + 8] * 128;
;     tab[sub] = make_uint2(__float_as_uint(tops[base + 16 + sub]), (unsigned)topi[base + 16 + sub]);
;     tab[sub + 8] = make_uint2(__float_as_uint(tops[base + 24 + sub]), (unsigned)topi[base + 24 + sub]);
;     asm volatile("s_waitcnt lgkmcnt(0)" ::: "memory");
;     const uint2 f0 = tab[0];
;     float c0 = s1r0 + __uint_as_float(f0.x), c1 = s1r1 + __uint_as_float(f0.x);
;     int e0c = i1r0 + (int)f0.y, e1c = i1r1 + (int)f0.y;
;     int p0 = 0, p1 = 0;
;     int es0 = 0, es1 = 0; float ss0 = 0.f, ss1 = 0.f;
;     for (int k = 0; k < 16; ++k) {
;       const bool r1 = c1 > c0;
;       const float ml = r1 ? c1 : c0;
;       const float m = row8_max(ml);
;       const unsigned long long bal = __ballot(ml == m);
;       const unsigned gbits = (unsigned)(bal >> gb) & 0xffu;
;       const int first = __ffs((int)gbits) - 1;
;       const int ewin = __shfl(r1 ? e1c : e0c, gb + first);
;       if (sub == (k & 7)) { if (k < 8) { es0 = ewin; ss0 = m; } else { es1 = ewin; ss1 = m; } }
;       const bool win = (sub == first);
;       const int pn = (r1 ? p1 : p0) + 1;
;       const uint2 f = tab[pn < 16 ? pn : 15];
.LBB0_528:
	s_waitcnt vmcnt(0)
	v_mov_b32_e32 v10, v184
	v_mov_b32_e32 v11, v185
	v_mov_b32_e32 v12, v186
	v_mov_b32_e32 v13, v187
	v_mov_b32_e32 v22, v188
	v_mov_b32_e32 v23, v189
	v_mov_b32_e32 v24, v190
	v_mov_b32_e32 v25, v191
	v_lshl_add_u64 v[200:201], s[92:93], 0, v[4:5]
	v_lshl_add_u64 v[200:201], v[200:201], 0, s[26:27]
	v_lshl_add_u64 v[200:201], v[200:201], 0, s[28:29]
	global_load_dwordx4 v[184:187], v[200:201], off
	global_load_dwordx4 v[188:191], v[200:201], off offset:16
	v_lshlrev_b32_e32 v21, 16, v10
	v_and_b32_e32 v10, 0xffff0000, v10
	v_lshlrev_b32_e32 v26, 16, v11
	v_and_b32_e32 v11, 0xffff0000, v11
	v_lshlrev_b32_e32 v27, 16, v12
	v_and_b32_e32 v12, 0xffff0000, v12
	v_lshlrev_b32_e32 v28, 16, v13
	v_and_b32_e32 v13, 0xffff0000, v13
	v_lshlrev_b32_e32 v29, 16, v22
	v_and_b32_e32 v22, 0xffff0000, v22
	v_lshlrev_b32_e32 v30, 16, v23
	v_mul_f32_e32 v21, 0x41400000, v21
	v_mul_f32_e32 v10, 0x41400000, v10
	v_mul_f32_e32 v26, 0x41400000, v26
	v_mul_f32_e32 v11, 0x41400000, v11
	v_mul_f32_e32 v12, 0x41400000, v12
	v_mul_f32_e32 v28, 0x41400000, v28
	v_and_b32_e32 v23, 0xffff0000, v23
	v_mul_f32_e32 v27, 0x41400000, v27
	v_mul_f32_e32 v13, 0x41400000, v13
	v_mul_f32_e32 v22, 0x41400000, v22
	v_mul_f32_e32 v30, 0x41400000, v30
	v_rndne_f32_e32 v21, v21
	v_rndne_f32_e32 v10, v10
	v_rndne_f32_e32 v26, v26
	v_rndne_f32_e32 v11, v11
	v_rndne_f32_e32 v12, v12
	v_rndne_f32_e32 v28, v28
	v_mul_f32_e32 v29, 0x41400000, v29
	v_mul_f32_e32 v23, 0x41400000, v23
	v_rndne_f32_e32 v27, v27
	v_rndne_f32_e32 v13, v13
	v_rndne_f32_e32 v22, v22
	v_rndne_f32_e32 v30, v30
	v_cvt_i32_f32_e32 v21, v21
	v_cvt_i32_f32_e32 v10, v10
	v_cvt_i32_f32_e32 v26, v26
	v_cvt_i32_f32_e32 v11, v11
	v_cvt_i32_f32_e32 v12, v12
	v_cvt_i32_f32_e32 v28, v28
	v_rndne_f32_e32 v29, v29
	v_rndne_f32_e32 v23, v23
	v_cvt_i32_f32_e32 v27, v27
	v_cvt_i32_f32_e32 v13, v13
	v_cvt_i32_f32_e32 v22, v22
	v_cvt_i32_f32_e32 v30, v30
	v_cvt_i32_f32_e32 v29, v29
	v_cvt_i32_f32_e32 v23, v23
	v_med3_i32 v21, v21, s21, v19
	v_med3_i32 v10, v10, s21, v19
	v_med3_i32 v26, v26, s21, v19
	v_med3_i32 v11, v11, s21, v19
	v_med3_i32 v12, v12, s21, v19
	v_med3_i32 v28, v28, s21, v19
	v_med3_i32 v27, v27, s21, v19
	v_med3_i32 v13, v13, s21, v19
	v_med3_i32 v22, v22, s21, v19
	v_med3_i32 v30, v30, s21, v19
	v_lshlrev_b32_e32 v10, 8, v10
	v_lshlrev_b32_e32 v26, 16, v26
	v_perm_b32 v11, v11, v21, s25
	v_lshlrev_b32_e32 v12, 8, v12
	v_lshlrev_b32_e32 v21, 16, v28
	v_lshlrev_b32_e32 v31, 16, v24
	v_and_b32_e32 v24, 0xffff0000, v24
	v_lshlrev_b32_e32 v32, 16, v25
	v_med3_i32 v29, v29, s21, v19
	v_med3_i32 v23, v23, s21, v19
	v_perm_b32 v13, v13, v27, s25
	v_lshlrev_b32_e32 v22, 8, v22
	v_lshlrev_b32_e32 v27, 16, v30
	v_and_b32_e32 v10, 0xff00, v10
	v_and_b32_e32 v26, 0xff0000, v26
	v_and_b32_e32 v12, 0xff00, v12
	v_and_b32_e32 v21, 0xff0000, v21
	v_and_b32_e32 v25, 0xffff0000, v25
	v_perm_b32 v23, v23, v29, s25
	v_and_b32_e32 v22, 0xff00, v22
	v_and_b32_e32 v27, 0xff0000, v27
	v_or3_b32 v10, v11, v10, v26
	v_or3_b32 v11, v13, v12, v21
	v_mul_f32_e32 v13, 0x41400000, v24
	v_mul_f32_e32 v21, 0x41400000, v32
	v_mul_f32_e32 v31, 0x41400000, v31
	v_or3_b32 v12, v23, v22, v27
	v_rndne_f32_e32 v13, v13
	v_rndne_f32_e32 v21, v21
	v_mul_f32_e32 v22, 0x41400000, v25
	v_rndne_f32_e32 v31, v31
	v_cvt_i32_f32_e32 v13, v13
	v_cvt_i32_f32_e32 v21, v21
	v_rndne_f32_e32 v22, v22
	v_cvt_i32_f32_e32 v31, v31
	v_cvt_i32_f32_e32 v22, v22
	v_med3_i32 v13, v13, s21, v19
	v_med3_i32 v21, v21, s21, v19
	v_med3_i32 v23, v31, s21, v19
	v_med3_i32 v22, v22, s21, v19
	v_lshlrev_b32_e32 v13, 8, v13
	v_lshlrev_b32_e32 v21, 16, v21
	v_and_b32_e32 v13, 0xff00, v13
	v_and_b32_e32 v21, 0xff0000, v21
	v_perm_b32 v22, v22, v23, s25
	v_or3_b32 v13, v22, v13, v21
	v_lshl_add_u64 v[22:23], s[92:93], 0, v[6:7]
	global_store_dwordx4 v[22:23], v[10:13], off
	v_mov_b32_e32 v30, 0
	s_nop 0
	v_mov_b32_e32 v21, v192
	v_mov_b32_e32 v24, v193
	v_mov_b32_e32 v25, v194
	v_mov_b32_e32 v27, v195
	v_mov_b32_e32 v26, v196
	v_mov_b32_e32 v10, v197
	v_mov_b32_e32 v13, v198
	v_mov_b32_e32 v12, v199
	v_lshl_add_u64 v[202:203], s[92:93], 0, v[8:9]
	v_lshl_add_u64 v[202:203], v[202:203], 0, s[30:31]
	v_add_co_u32_e32 v204, vcc, 0x6b20000, v202
	s_nop 1
	v_addc_co_u32_e32 v205, vcc, 0, v203, vcc
	v_add_co_u32_e32 v202, vcc, 0x8b20000, v202
	s_nop 1
	v_addc_co_u32_e32 v203, vcc, 0, v203, vcc
	global_load_dword v192, v[202:203], off offset:32
	global_load_dword v193, v[204:205], off offset:64
	global_load_dword v194, v[202:203], off offset:64
	global_load_dword v195, v[202:203], off offset:96
	global_load_dword v196, v[204:205], off offset:96
	global_load_dword v197, v[202:203], off
	global_load_dword v198, v[204:205], off
	global_load_dword v199, v[204:205], off offset:32
	ds_write2_b64 v17, v[24:25], v[26:27] offset1:8
	s_waitcnt lgkmcnt(0)
	ds_read_b64 v[22:23], v16
	v_lshlrev_b32_e32 v25, 7, v10
	v_lshlrev_b32_e32 v26, 7, v21
	s_waitcnt lgkmcnt(0)
	v_pk_add_f32 v[10:11], v[12:13], v[22:23] op_sel_hi:[1,0]
	s_nop 0
	v_cmp_gt_f32_e32 vcc, v10, v11
	v_add_u32_e32 v21, v23, v25
	v_add_u32_e32 v22, v23, v26
	v_cndmask_b32_e32 v24, v11, v10, vcc
	s_nop 1
	v_max_f32_dpp v23, v24, v24 quad_perm:[1,0,3,2] row_mask:0xf bank_mask:0xf
	s_nop 1
	v_max_f32_dpp v23, v23, v23 quad_perm:[2,3,0,1] row_mask:0xf bank_mask:0xf
	s_nop 1
	v_max_f32_dpp v23, v23, v23 row_half_mirror row_mask:0xf bank_mask:0xf
	s_nop 0
	v_cmp_eq_f32_e64 s[0:1], v24, v23
	v_cndmask_b32_e32 v24, v21, v22, vcc
	s_nop 0
	v_lshrrev_b64 v[28:29], v0, s[0:1]
	v_ffbl_b32_sdwa v27, v28 dst_sel:DWORD dst_unused:UNUSED_PAD src0_sel:BYTE_0
	v_add_u32_e32 v28, v27, v0
	v_and_or_b32 v28, v28, 63, v20
	v_lshlrev_b32_e32 v28, 2, v28
	ds_bpermute_b32 v24, v28, v24
	v_cmp_eq_u32_e64 s[0:1], v15, v27
	v_mov_b32_e32 v27, 0
	s_and_saveexec_b64 s[54:55], s[0:1]
	s_cbranch_execz .LBB0_530
	ds_read_b64 v[28:29], v16 offset:8
	v_cndmask_b32_e32 v27, v13, v12, vcc
	s_xor_b64 s[0:1], vcc, -1
	v_cndmask_b32_e64 v30, 0, 1, s[0:1]
	s_waitcnt lgkmcnt(0)
	v_add_f32_e32 v28, v27, v28
	v_cndmask_b32_e32 v27, v25, v26, vcc
	v_add_u32_e32 v29, v29, v27
	v_cndmask_b32_e64 v27, 0, 1, vcc
	v_cndmask_b32_e32 v22, v22, v29, vcc
	v_cndmask_b32_e32 v21, v29, v21, vcc
	v_cndmask_b32_e32 v10, v10, v28, vcc
	v_cndmask_b32_e32 v11, v28, v11, vcc
